# hyena_post context-row convolution: wave-uniform linear-index fast paths for 8-tap blocks on one side of d=0
# speedup vs baseline: 1.0054x; 1.0006x over previous
; #define TIDX tid_fn()
; __device__ __forceinline__ void ph_hyena_post(const Params& P, char* smem) {
;     ...
;       for (int i = TIDX; i < CTX_LEN * CT_; i += NTHR) {
;         int t = i / CT_, c = i % CT_;
;         float acc = 0.f;
;         for (int s = 0; s < CTX_LEN; ++s) {
;           int d = t - s;
;           float g = d >= 0 ? gs[(c * 2 + 0) * GLD + d] : gs[(c * 2 + 1) * GLD - d];
;           acc += zs[s * (CT_ + 1) + c] * g;
;         }
.LBB0_1130:
	v_add_u32_e32 v7, s4, v3
	v_add_u32_e32 v25, 0xffffff00, v7
	v_cmp_le_i32_e32 vcc, 7, v25
	s_cmp_eq_u64 vcc, exec
	s_cbranch_scc1 .Lhpc_pos
	v_cmp_gt_i32_e32 vcc, 0, v25
	s_cmp_eq_u64 vcc, exec
	s_cbranch_scc1 .Lhpc_neg
	s_branch .Lhpc_mixed
.Lhpc_pos:
	v_add_u32_e32 v18, s4, v6
	v_add_u32_e32 v18, 0xfffffef9, v18
	v_lshlrev_b32_e32 v18, 2, v18
	ds_read2_b32 v[8:9], v4 offset1:9
	ds_read2_b32 v[12:13], v4 offset0:18 offset1:27
	ds_read2_b32 v[14:15], v4 offset0:36 offset1:45
	ds_read2_b32 v[16:17], v4 offset0:54 offset1:63
	ds_read_b32 v11, v18 offset:9244
	ds_read_b32 v19, v18 offset:9240
	ds_read_b32 v20, v18 offset:9236
	ds_read_b32 v21, v18 offset:9232
	ds_read_b32 v22, v18 offset:9228
	ds_read_b32 v23, v18 offset:9224
	ds_read_b32 v24, v18 offset:9220
	ds_read_b32 v7, v18 offset:9216
	s_waitcnt lgkmcnt(7)
	v_fmac_f32_e32 v10, v11, v8
	s_waitcnt lgkmcnt(6)
	v_fmac_f32_e32 v10, v19, v9
	s_waitcnt lgkmcnt(5)
	v_fmac_f32_e32 v10, v20, v12
	s_waitcnt lgkmcnt(4)
	v_fmac_f32_e32 v10, v21, v13
	s_waitcnt lgkmcnt(3)
	v_fmac_f32_e32 v10, v22, v14
	s_waitcnt lgkmcnt(2)
	v_fmac_f32_e32 v10, v23, v15
	s_waitcnt lgkmcnt(1)
	v_fmac_f32_e32 v10, v24, v16
	s_waitcnt lgkmcnt(0)
	v_fmac_f32_e32 v10, v7, v17
	s_add_i32 s4, s4, -8
	v_add_u32_e32 v4, 0x120, v4
	v_add_u32_e32 v5, 8, v5
	s_cmp_eq_u32 s4, 0
	s_cbranch_scc0 .LBB0_1130
	s_branch .Lhpc_exit
.Lhpc_neg:
	v_add_u32_e32 v18, -7, v5
	v_lshlrev_b32_e32 v18, 2, v18
	ds_read2_b32 v[8:9], v4 offset1:9
	ds_read2_b32 v[12:13], v4 offset0:18 offset1:27
	ds_read2_b32 v[14:15], v4 offset0:36 offset1:45
	ds_read2_b32 v[16:17], v4 offset0:54 offset1:63
	ds_read_b32 v11, v18 offset:9216
	ds_read_b32 v19, v18 offset:9220
	ds_read_b32 v20, v18 offset:9224
	ds_read_b32 v21, v18 offset:9228
	ds_read_b32 v22, v18 offset:9232
	ds_read_b32 v23, v18 offset:9236
	ds_read_b32 v24, v18 offset:9240
	ds_read_b32 v7, v18 offset:9244
	s_waitcnt lgkmcnt(7)
	v_fmac_f32_e32 v10, v11, v8
	s_waitcnt lgkmcnt(6)
	v_fmac_f32_e32 v10, v19, v9
	s_waitcnt lgkmcnt(5)
	v_fmac_f32_e32 v10, v20, v12
	s_waitcnt lgkmcnt(4)
	v_fmac_f32_e32 v10, v21, v13
	s_waitcnt lgkmcnt(3)
	v_fmac_f32_e32 v10, v22, v14
	s_waitcnt lgkmcnt(2)
	v_fmac_f32_e32 v10, v23, v15
	s_waitcnt lgkmcnt(1)
	v_fmac_f32_e32 v10, v24, v16
	s_waitcnt lgkmcnt(0)
	v_fmac_f32_e32 v10, v7, v17
	s_add_i32 s4, s4, -8
	v_add_u32_e32 v4, 0x120, v4
	v_add_u32_e32 v5, 8, v5
	s_cmp_eq_u32 s4, 0
	s_cbranch_scc0 .LBB0_1130
	s_branch .Lhpc_exit

; __device__ __forceinline__ float hy_short(const Params& P, const h16* p, int rbase, int L, int t, int col) {
;   float acc = P.hy_short_b[col];
; #pragma unroll
;   for (int k = 0; k < 3; ++k) {
;     int tt = t + k - 1;
;     if (tt >= 0 && tt < L) acc += P.hy_short_w[k * (3 * HY_CH) + col] * (float)p[(size_t)(rbase + tt) * NP_EV + col];
;   }
;   return acc;
; __device__ __forceinline__ void ph_hyena_post(const Params& P, char* smem) {
;     ...
;         float x0 = hy_short(P, p, rbase, CTX_LEN, t, c0 + c);
;         mix[(size_t)(rbase + t) * D + c0 + c] = (h16)(x0 * (acc + zs[t * (CT_ + 1) + c] * P.hy_bias[c0 + c]));
.Lhpc_exit:
	v_add_u32_e32 v4, s38, v2
	v_ashrrev_i32_e32 v5, 31, v4
	v_lshl_add_u64 v[6:7], v[4:5], 2, s[18:19]
	global_load_dword v11, v[6:7], off
	v_add_u32_e32 v8, -1, v3
	v_lshl_add_u64 v[6:7], v[4:5], 1, s[22:23]
	v_cmp_gt_u32_e32 vcc, s47, v8
	v_lshl_add_u64 v[8:9], v[4:5], 2, s[16:17]
	s_and_saveexec_b64 s[4:5], vcc
	s_cbranch_execz .LBB0_1133
	v_add_u32_e32 v12, s30, v3
	v_mul_lo_u32 v26, v12, s48
	v_lshl_add_u64 v[12:13], v[6:7], 0, v[26:27]
	global_load_dword v14, v[8:9], off
	s_nop 0
	global_load_ushort v12, v[12:13], off
	s_waitcnt vmcnt(0)
	v_fma_mix_f32 v11, v14, v12, v11 op_sel_hi:[0,1,0]
